# adds: fewer counted waits in the GLA chunk loop (one per two consumers)
# speedup vs baseline: 1.0003x; 1.0003x over previous
.LBB0_1317:
	s_waitcnt vmcnt(45)
	v_perm_b32 v26, v115, v115, v32
	v_add_f32_e32 v176, 0, v26
	v_perm_b32 v26, v119, v119, v32
	v_add_f32_e32 v177, v176, v26
	s_waitcnt vmcnt(39)
	v_perm_b32 v26, v124, v124, v32
	v_add_f32_e32 v178, v177, v26
	v_perm_b32 v26, v132, v132, v32
	v_add_f32_e32 v179, v178, v26
	s_waitcnt vmcnt(33)
	v_perm_b32 v26, v136, v136, v32
	v_add_f32_e32 v180, v179, v26
	v_perm_b32 v26, v143, v143, v32
	v_add_f32_e32 v181, v180, v26
	s_waitcnt vmcnt(27)
	v_perm_b32 v26, v146, v146, v32
	v_add_f32_e32 v182, v181, v26
	v_perm_b32 v26, v149, v149, v32
	v_add_f32_e32 v183, v182, v26
	s_waitcnt vmcnt(21)
	v_perm_b32 v26, v152, v152, v32
	v_add_f32_e32 v184, v183, v26
	v_perm_b32 v26, v155, v155, v32
	v_add_f32_e32 v185, v184, v26
	s_waitcnt vmcnt(15)
	v_perm_b32 v26, v158, v158, v32
	v_add_f32_e32 v186, v185, v26
	v_perm_b32 v26, v161, v161, v32
	v_add_f32_e32 v187, v186, v26
	s_waitcnt vmcnt(9)
	v_perm_b32 v26, v164, v164, v32
	v_add_f32_e32 v188, v187, v26
	v_perm_b32 v26, v167, v167, v32
	v_add_f32_e32 v189, v188, v26
	s_waitcnt vmcnt(3)
	v_perm_b32 v26, v170, v170, v32
	v_add_f32_e32 v190, v189, v26
	v_perm_b32 v26, v173, v173, v32
	v_add_f32_e32 v191, v190, v26
	ds_bpermute_b32 v26, v53, v191
	ds_bpermute_b32 v28, v54, v191
	ds_bpermute_b32 v27, v55, v191
	ds_bpermute_b32 v29, v56, v191
	v_cvt_pk_bf16_f32 v22, v2, v3
	v_cvt_pk_bf16_f32 v23, v4, v5
	v_cvt_pk_bf16_f32 v24, v14, v15
	v_cvt_pk_bf16_f32 v25, v16, v17
	s_add_i32 s78, s74, 0x100
	s_add_i32 s32, s75, 0xffffe000
	s_cmp_lg_u32 s70, 0
	s_cselect_b32 s78, s78, s32
	s_cselect_b32 s32, s74, s75
	s_add_i32 s32, s32, s65
	s_add_i32 s78, s78, s56
	s_cmp_gt_u32 s57, 2
	s_cselect_b32 s32, s32, s78
	s_cmp_eq_u32 s75, -1
	s_cselect_b32 s32, s76, s32
	s_add_i32 s32, s32, s91
	s_lshl_b32 s32, s32, 13
	s_add_u32 s80, s82, s32
	s_addc_u32 s81, s83, 0
	s_waitcnt lgkmcnt(0)
	s_barrier
	ds_write2_b64 v103, v[22:23], v[24:25] offset1:4
	v_cvt_pk_bf16_f32 v22, v6, v7
	v_cvt_pk_bf16_f32 v23, v8, v9
	v_cvt_pk_bf16_f32 v24, v10, v11
	v_cvt_pk_bf16_f32 v25, v12, v13
	ds_write2_b64 v103, v[22:23], v[24:25] offset0:8 offset1:12
	v_cndmask_b32_e64 v22, v26, 0, s[0:1]
	v_cndmask_b32_e64 v23, 0, v28, s[2:3]
	v_add_f32_e32 v22, v22, v23
	v_cndmask_b32_e64 v23, 0, v27, s[4:5]
	v_add_f32_e32 v192, v22, v23
	v_pk_add_f32 v[22:23], v[26:27], v[28:29]
	v_add_f32_e32 v22, v22, v23
	v_add_f32_e32 v23, v176, v192
	v_exp_f32_e32 v25, v23
	v_perm_b32 v24, v116, v116, v32
	v_exp_f32_e64 v26, -v23
	v_exp_f32_e32 v22, v22
	v_mul_f32_e32 v23, v25, v24
	v_cvt_pk_bf16_f32 v23, v23, s0
	ds_write_b16 v64, v23
	v_add_f32_e32 v23, v177, v192
	v_exp_f32_e32 v24, v23
	v_exp_f32_e64 v27, -v23
	v_perm_b32 v25, v121, v121, v32
	v_perm_b32 v29, v122, v122, v1
	v_perm_b32 v28, v118, v118, v32
	global_load_dword v115, v110, s[80:81]
	global_load_dword v116, v111, s[80:81]
	global_load_dword v118, v112, s[80:81]
	s_add_u32 s80, s80, s98
	s_addc_u32 s81, s81, s99
	global_load_dword v119, v110, s[80:81]
	global_load_dword v121, v111, s[80:81]
	global_load_dword v122, v112, s[80:81]
	s_add_u32 s80, s80, s98
	s_addc_u32 s81, s81, s99
	v_mul_f32_e32 v23, v24, v25
	v_mul_f32_e32 v24, v26, v28
	v_cvt_pk_bf16_f32 v23, v23, s0
	v_cvt_pk_bf16_f32 v24, v24, s0
	ds_write_b16 v64, v24 offset:17408
	v_pk_mul_f32 v[24:25], v[22:23], v[26:27] op_sel_hi:[0,1]
	ds_write_b16 v65, v23
	v_mul_f32_e32 v23, v27, v29
	v_cvt_pk_bf16_f32 v23, v23, s0
	ds_write_b16 v65, v23 offset:17408
	v_add_f32_e32 v23, v178, v192
	v_pk_mul_f32 v[24:25], v[24:25], v[28:29]
	v_exp_f32_e32 v28, v23
	v_perm_b32 v27, v127, v127, v32
	v_exp_f32_e64 v26, -v23
	v_mul_f32_e32 v23, v28, v27
	v_cvt_pk_bf16_f32 v23, v23, s0
	ds_write_b16 v66, v23
	v_add_f32_e32 v23, v179, v192
	v_exp_f32_e32 v28, v23
	v_perm_b32 v177, v133, v133, v32
	v_exp_f32_e64 v27, -v23
	v_mul_f32_e32 v23, v28, v177
	v_perm_b32 v28, v130, v130, v32
	global_load_dword v124, v110, s[80:81]
	global_load_dword v127, v111, s[80:81]
	global_load_dword v130, v112, s[80:81]
	s_add_u32 s80, s80, s98
	s_addc_u32 s81, s81, s99
	v_mul_f32_e32 v176, v26, v28
	v_cvt_pk_bf16_f32 v23, v23, s0
	v_perm_b32 v29, v135, v135, v1
	global_load_dword v132, v110, s[80:81]
	global_load_dword v133, v111, s[80:81]
	global_load_dword v135, v112, s[80:81]
	s_add_u32 s80, s80, s98
	s_addc_u32 s81, s81, s99
	v_cvt_pk_bf16_f32 v176, v176, s0
	ds_write_b16 v66, v176 offset:17408
	v_pk_mul_f32 v[176:177], v[22:23], v[26:27] op_sel_hi:[0,1]
	ds_write_b16 v67, v23
	v_mul_f32_e32 v23, v27, v29
	v_cvt_pk_bf16_f32 v23, v23, s0
	ds_write_b16 v67, v23 offset:17408
	v_add_f32_e32 v23, v180, v192
	v_pk_mul_f32 v[176:177], v[176:177], v[28:29]
	v_exp_f32_e32 v28, v23
	v_perm_b32 v27, v137, v137, v32
	v_exp_f32_e64 v26, -v23
	v_mul_f32_e32 v23, v28, v27
	v_cvt_pk_bf16_f32 v23, v23, s0
	ds_write_b16 v68, v23
	v_add_f32_e32 v23, v181, v192
	v_exp_f32_e32 v28, v23
	v_perm_b32 v179, v144, v144, v32
	v_exp_f32_e64 v27, -v23
	v_mul_f32_e32 v23, v28, v179
	v_perm_b32 v28, v138, v138, v32
	global_load_dword v136, v110, s[80:81]
	global_load_dword v137, v111, s[80:81]
	global_load_dword v138, v112, s[80:81]
	s_add_u32 s80, s80, s98
	s_addc_u32 s81, s81, s99
	v_mul_f32_e32 v178, v26, v28
	v_cvt_pk_bf16_f32 v23, v23, s0
	v_perm_b32 v29, v145, v145, v1
	global_load_dword v143, v110, s[80:81]
	global_load_dword v144, v111, s[80:81]
	global_load_dword v145, v112, s[80:81]
	s_add_u32 s80, s80, s98
	s_addc_u32 s81, s81, s99
	v_cvt_pk_bf16_f32 v178, v178, s0
	ds_write_b16 v68, v178 offset:17408
	v_pk_mul_f32 v[178:179], v[22:23], v[26:27] op_sel_hi:[0,1]
	ds_write_b16 v69, v23
	v_mul_f32_e32 v23, v27, v29
	v_cvt_pk_bf16_f32 v23, v23, s0
	ds_write_b16 v69, v23 offset:17408
	v_add_f32_e32 v23, v182, v192
	v_pk_mul_f32 v[178:179], v[178:179], v[28:29]
	v_exp_f32_e32 v28, v23
	v_perm_b32 v27, v147, v147, v32
	v_exp_f32_e64 v26, -v23
	v_mul_f32_e32 v23, v28, v27
	v_cvt_pk_bf16_f32 v23, v23, s0
	ds_write_b16 v70, v23
	v_add_f32_e32 v23, v183, v192
	v_exp_f32_e32 v28, v23
	v_perm_b32 v181, v150, v150, v32
	v_exp_f32_e64 v27, -v23
	v_mul_f32_e32 v23, v28, v181
	v_perm_b32 v28, v148, v148, v32
	global_load_dword v146, v110, s[80:81]
	global_load_dword v147, v111, s[80:81]
	global_load_dword v148, v112, s[80:81]
	s_add_u32 s80, s80, s98
	s_addc_u32 s81, s81, s99
	v_mul_f32_e32 v180, v26, v28
	v_cvt_pk_bf16_f32 v23, v23, s0
	v_perm_b32 v29, v151, v151, v1
	global_load_dword v149, v110, s[80:81]
	global_load_dword v150, v111, s[80:81]
	global_load_dword v151, v112, s[80:81]
	s_add_u32 s80, s80, s98
	s_addc_u32 s81, s81, s99
	v_cvt_pk_bf16_f32 v180, v180, s0
	ds_write_b16 v70, v180 offset:17408
	v_pk_mul_f32 v[180:181], v[22:23], v[26:27] op_sel_hi:[0,1]
	ds_write_b16 v71, v23
	v_mul_f32_e32 v23, v27, v29
	v_cvt_pk_bf16_f32 v23, v23, s0
	ds_write_b16 v71, v23 offset:17408
	v_add_f32_e32 v23, v184, v192
	v_pk_mul_f32 v[180:181], v[180:181], v[28:29]
	v_exp_f32_e32 v28, v23
	v_perm_b32 v27, v153, v153, v32
	v_exp_f32_e64 v26, -v23
	v_mul_f32_e32 v23, v28, v27
	v_cvt_pk_bf16_f32 v23, v23, s0
	ds_write_b16 v72, v23
	v_add_f32_e32 v23, v185, v192
	v_exp_f32_e32 v28, v23
	v_perm_b32 v183, v156, v156, v32
	v_exp_f32_e64 v27, -v23
	v_mul_f32_e32 v23, v28, v183
	v_perm_b32 v28, v154, v154, v32
	global_load_dword v152, v110, s[80:81]
	global_load_dword v153, v111, s[80:81]
	global_load_dword v154, v112, s[80:81]
	s_add_u32 s80, s80, s98
	s_addc_u32 s81, s81, s99
	v_mul_f32_e32 v182, v26, v28
	v_cvt_pk_bf16_f32 v23, v23, s0
	v_perm_b32 v29, v157, v157, v1
	global_load_dword v155, v110, s[80:81]
	global_load_dword v156, v111, s[80:81]
	global_load_dword v157, v112, s[80:81]
	s_add_u32 s80, s80, s98
	s_addc_u32 s81, s81, s99
	v_cvt_pk_bf16_f32 v182, v182, s0
	ds_write_b16 v72, v182 offset:17408
	v_pk_mul_f32 v[182:183], v[22:23], v[26:27] op_sel_hi:[0,1]
	ds_write_b16 v73, v23
	v_mul_f32_e32 v23, v27, v29
	v_cvt_pk_bf16_f32 v23, v23, s0
	ds_write_b16 v73, v23 offset:17408
	v_add_f32_e32 v23, v186, v192
	v_pk_mul_f32 v[182:183], v[182:183], v[28:29]
	v_exp_f32_e32 v28, v23
	v_perm_b32 v27, v159, v159, v32
	v_exp_f32_e64 v26, -v23
	v_mul_f32_e32 v23, v28, v27
	v_cvt_pk_bf16_f32 v23, v23, s0
	ds_write_b16 v74, v23
	v_add_f32_e32 v23, v187, v192
	v_exp_f32_e32 v28, v23
	v_perm_b32 v185, v162, v162, v32
	v_exp_f32_e64 v27, -v23
	v_mul_f32_e32 v23, v28, v185
	v_perm_b32 v28, v160, v160, v32
	global_load_dword v158, v110, s[80:81]
	global_load_dword v159, v111, s[80:81]
	global_load_dword v160, v112, s[80:81]
	s_add_u32 s80, s80, s98
	s_addc_u32 s81, s81, s99
	v_mul_f32_e32 v184, v26, v28
	v_cvt_pk_bf16_f32 v23, v23, s0
	v_perm_b32 v29, v163, v163, v1
	global_load_dword v161, v110, s[80:81]
	global_load_dword v162, v111, s[80:81]
	global_load_dword v163, v112, s[80:81]
	s_add_u32 s80, s80, s98
	s_addc_u32 s81, s81, s99
	v_cvt_pk_bf16_f32 v184, v184, s0
	ds_write_b16 v74, v184 offset:17408
	v_pk_mul_f32 v[184:185], v[22:23], v[26:27] op_sel_hi:[0,1]
	ds_write_b16 v75, v23
	v_mul_f32_e32 v23, v27, v29
	v_cvt_pk_bf16_f32 v23, v23, s0
	ds_write_b16 v75, v23 offset:17408
	v_add_f32_e32 v23, v188, v192
	v_pk_mul_f32 v[184:185], v[184:185], v[28:29]
	v_exp_f32_e32 v28, v23
	v_perm_b32 v27, v165, v165, v32
	v_exp_f32_e64 v26, -v23
	v_mul_f32_e32 v23, v28, v27
	v_cvt_pk_bf16_f32 v23, v23, s0
	ds_write_b16 v76, v23
	v_add_f32_e32 v23, v189, v192
	v_exp_f32_e32 v28, v23
	v_perm_b32 v187, v168, v168, v32
	v_exp_f32_e64 v27, -v23
	v_mul_f32_e32 v23, v28, v187
	v_perm_b32 v28, v166, v166, v32
	global_load_dword v164, v110, s[80:81]
	global_load_dword v165, v111, s[80:81]
	global_load_dword v166, v112, s[80:81]
	s_add_u32 s80, s80, s98
	s_addc_u32 s81, s81, s99
	v_mul_f32_e32 v186, v26, v28
	v_cvt_pk_bf16_f32 v23, v23, s0
	v_perm_b32 v29, v169, v169, v1
	global_load_dword v167, v110, s[80:81]
	global_load_dword v168, v111, s[80:81]
	global_load_dword v169, v112, s[80:81]
	s_add_u32 s80, s80, s98
	s_addc_u32 s81, s81, s99
	v_cvt_pk_bf16_f32 v186, v186, s0
	ds_write_b16 v76, v186 offset:17408
	v_pk_mul_f32 v[186:187], v[22:23], v[26:27] op_sel_hi:[0,1]
	ds_write_b16 v77, v23
	v_mul_f32_e32 v23, v27, v29
	v_cvt_pk_bf16_f32 v23, v23, s0
	ds_write_b16 v77, v23 offset:17408
	v_add_f32_e32 v23, v190, v192
	v_exp_f32_e32 v27, v23
	v_perm_b32 v26, v171, v171, v32
	v_pk_mul_f32 v[186:187], v[186:187], v[28:29]
	v_exp_f32_e64 v28, -v23
	v_mul_f32_e32 v23, v27, v26
	v_cvt_pk_bf16_f32 v23, v23, s0
	ds_write_b16 v78, v23
	v_add_f32_e32 v23, v191, v192
	v_exp_f32_e32 v26, v23
	s_waitcnt vmcnt(43)
	v_exp_f32_e64 v29, -v23
	v_perm_b32 v27, v174, v174, v32
	v_perm_b32 v189, v175, v175, v1
	v_perm_b32 v188, v172, v172, v32
	global_load_dword v170, v110, s[80:81]
	global_load_dword v171, v111, s[80:81]
	global_load_dword v172, v112, s[80:81]
	s_add_u32 s80, s80, s98
	s_addc_u32 s81, s81, s99
	global_load_dword v173, v110, s[80:81]
	global_load_dword v174, v111, s[80:81]
	global_load_dword v175, v112, s[80:81]
	v_mul_f32_e32 v23, v26, v27
	v_mul_f32_e32 v26, v28, v188
	v_cvt_pk_bf16_f32 v23, v23, s0
	v_cvt_pk_bf16_f32 v26, v26, s0
	ds_write_b16 v78, v26 offset:17408
	ds_write_b16 v79, v23
	v_mul_f32_e32 v23, v29, v189
	v_cvt_pk_bf16_f32 v23, v23, s0
	v_pk_mul_f32 v[28:29], v[22:23], v[28:29] op_sel_hi:[0,1]
	v_cvt_pk_bf16_f32 v24, v24, v25
	v_cvt_pk_bf16_f32 v25, v176, v177
	v_cvt_pk_bf16_f32 v26, v178, v179
	v_cvt_pk_bf16_f32 v27, v180, v181
	v_pk_mul_f32 v[28:29], v[28:29], v[188:189]
	ds_write_b16 v79, v23 offset:17408
	v_cvt_pk_bf16_f32 v176, v182, v183
	v_cvt_pk_bf16_f32 v177, v184, v185
	v_cvt_pk_bf16_f32 v178, v186, v187
	v_cvt_pk_bf16_f32 v179, v28, v29
	ds_write_b128 v57, v[24:27] offset:34816
	ds_write_b128 v57, v[176:179] offset:34832
	s_and_saveexec_b64 s[72:73], s[0:1]
	ds_write_b32 v61, v22
	s_or_b64 exec, exec, s[72:73]
	s_cmp_eq_u32 s75, -1
	s_mov_b32 s10, s76
	s_waitcnt vmcnt(48)
	ds_write_b16 v58, v18 offset:53248
	ds_write_b16_d16_hi v58, v18 offset:53392
	ds_write_b16 v58, v19 offset:53536
	ds_write_b16_d16_hi v58, v19 offset:53680
	ds_write_b16 v58, v20 offset:53824
	ds_write_b16_d16_hi v58, v20 offset:53968
	ds_write_b16 v58, v21 offset:54112
	ds_write_b16_d16_hi v59, v21 offset:53248
	s_cbranch_scc1 .LBB0_1325
	s_cmp_gt_u32 s57, 2
	s_mov_b64 s[72:73], -1
	s_cbranch_scc0 .LBB0_1322
	s_and_b64 s[10:11], s[70:71], exec
	s_cselect_b32 s10, s74, s75
	s_add_i32 s10, s10, s65
	s_mov_b64 s[72:73], 0

.LBB0_1325:
	s_cmp_gt_u32 s57, 3
	s_cselect_b64 s[72:73], -1, 0
	s_cmp_lt_u32 s57, 4
	s_waitcnt lgkmcnt(0)
	s_barrier
	s_cbranch_scc1 .LBB0_1331
	v_mov_b32_e32 v22, 0
	v_mov_b32_e32 v23, 0
	v_mov_b32_e32 v24, 0
	v_mov_b32_e32 v25, 0
	v_mov_b32_e32 v26, 0
	v_mov_b32_e32 v27, 0
	v_mov_b32_e32 v28, 0
	v_mov_b32_e32 v29, 0
	ds_read_b128 v[176:179], v81
	ds_read_b128 v[180:183], v80 offset:17408
	ds_read_b128 v[184:187], v83
	ds_read_b128 v[188:191], v82 offset:17408
	ds_read_b128 v[192:195], v84
	ds_read_b128 v[196:199], v80 offset:17536
	ds_read_b128 v[200:203], v86
	ds_read_b128 v[216:219], v85 offset:17408
	ds_read_b128 v[220:223], v87 offset:17408
	ds_read_b128 v[224:227], v88 offset:17408
	ds_read_b128 v[236:239], v89 offset:17408
	ds_read_b128 v[248:251], v90 offset:17408
	s_andn2_b64 vcc, exec, s[66:67]
	s_cbranch_vccnz .Lgl_p2a
	s_waitcnt lgkmcnt(4)
	v_mfma_f32_16x16x32_bf16 v[22:25], v[180:183], v[176:179], v[22:25]
	v_mfma_f32_16x16x32_bf16 v[22:25], v[188:191], v[184:187], v[22:25]
	v_mfma_f32_16x16x32_bf16 v[22:25], v[196:199], v[192:195], v[22:25]
	v_mfma_f32_16x16x32_bf16 v[22:25], v[216:219], v[200:203], v[22:25]
.Lgl_p2a:
	s_andn2_b64 vcc, exec, s[68:69]
	s_cbranch_vccnz .Lgl_p2b
	s_waitcnt lgkmcnt(0)
	v_mfma_f32_16x16x32_bf16 v[26:29], v[220:223], v[176:179], v[26:29]
	v_mfma_f32_16x16x32_bf16 v[26:29], v[224:227], v[184:187], v[26:29]
	v_mfma_f32_16x16x32_bf16 v[26:29], v[236:239], v[192:195], v[26:29]
	v_mfma_f32_16x16x32_bf16 v[26:29], v[248:251], v[200:203], v[26:29]

.LBB0_1331:
	s_waitcnt lgkmcnt(0)
	s_barrier
	ds_read_b128 v[26:29], v60 offset:53248
	ds_read_b128 v[22:25], v60 offset:53312
	s_andn2_b64 vcc, exec, s[72:73]
	s_cbranch_vccnz .Lgl_su
	ds_read_b128 v[176:179], v104 offset:62464
	ds_read_b128 v[180:183], v104 offset:62528
	ds_read_b128 v[184:187], v62
	ds_read_b128 v[188:191], v92
	ds_read_b128 v[192:195], v62 offset:64
	ds_read_b128 v[196:199], v93
	ds_read_b128 v[200:203], v62 offset:128
	ds_read_b128 v[216:219], v94
	ds_read_b128 v[220:223], v62 offset:192
	ds_read_b128 v[224:227], v95
	s_waitcnt lgkmcnt(8)
	v_mfma_f32_16x16x32_bf16 v[248:251], v[26:29], v[176:179], 0
	ds_read_b128 v[176:179], v105 offset:62464
	v_mfma_f32_16x16x32_bf16 v[248:251], v[22:25], v[180:183], v[248:251]
	ds_read_b128 v[180:183], v105 offset:62528
	s_waitcnt lgkmcnt(6)
	v_mfma_f32_16x16x32_bf16 v[248:251], v[184:187], v[188:191], v[248:251]
	ds_read_b128 v[188:191], v97
	v_mfma_f32_16x16x32_bf16 v[248:251], v[192:195], v[196:199], v[248:251]
	ds_read_b128 v[196:199], v98
	s_waitcnt lgkmcnt(4)
	v_mfma_f32_16x16x32_bf16 v[248:251], v[200:203], v[216:219], v[248:251]
	ds_read_b128 v[216:219], v99
	v_mfma_f32_16x16x32_bf16 v[248:251], v[220:223], v[224:227], v[248:251]
	ds_read_b128 v[224:227], v100
	s_waitcnt lgkmcnt(4)
	v_mfma_f32_16x16x32_bf16 v[236:239], v[26:29], v[176:179], 0
	ds_read_b128 v[176:179], v101
	v_mfma_f32_16x16x32_bf16 v[236:239], v[22:25], v[180:183], v[236:239]
	ds_read_b128 v[180:183], v106 offset:34816
	s_waitcnt lgkmcnt(4)
	v_mfma_f32_16x16x32_bf16 v[236:239], v[184:187], v[188:191], v[236:239]
	ds_read_b128 v[184:187], v106 offset:34880
	ds_read_b128 v[188:191], v101 offset:64
	v_mfma_f32_16x16x32_bf16 v[236:239], v[192:195], v[196:199], v[236:239]
	ds_read_b128 v[192:195], v107 offset:34816
	ds_read_b128 v[196:199], v107 offset:34880
	s_waitcnt lgkmcnt(6)
	v_mfma_f32_16x16x32_bf16 v[236:239], v[200:203], v[216:219], v[236:239]
	ds_read_b128 v[200:203], v101 offset:128
	ds_read_b128 v[216:219], v108 offset:34816
	v_mfma_f32_16x16x32_bf16 v[236:239], v[220:223], v[224:227], v[236:239]
	ds_read_b128 v[220:223], v108 offset:34880
	ds_read_b128 v[224:227], v101 offset:192
	s_waitcnt lgkmcnt(8)
	v_pk_mul_f32 v[4:5], v[4:5], v[178:179]
	v_pk_mul_f32 v[2:3], v[2:3], v[176:177]
	ds_read_b128 v[176:179], v109 offset:34816
	s_nop 0
	v_mfma_f32_16x16x32_bf16 v[2:5], v[180:183], v[26:29], v[2:5]
	ds_read_b128 v[180:183], v109 offset:34880
	s_waitcnt lgkmcnt(8)
	v_mfma_f32_16x16x32_bf16 v[2:5], v[184:187], v[22:25], v[2:5]
	v_pk_mul_f32 v[16:17], v[16:17], v[190:191]
	v_pk_mul_f32 v[14:15], v[14:15], v[188:189]
	s_nop 1
	s_waitcnt lgkmcnt(6)
	v_mfma_f32_16x16x32_bf16 v[14:17], v[192:195], v[26:29], v[14:17]
	v_mfma_f32_16x16x32_bf16 v[14:17], v[196:199], v[22:25], v[14:17]
	s_waitcnt lgkmcnt(4)
	v_pk_mul_f32 v[8:9], v[8:9], v[202:203]
	v_pk_mul_f32 v[6:7], v[6:7], v[200:201]
	s_nop 1
	v_mfma_f32_16x16x32_bf16 v[6:9], v[216:219], v[26:29], v[6:9]
	s_waitcnt lgkmcnt(2)
	v_mfma_f32_16x16x32_bf16 v[6:9], v[220:223], v[22:25], v[6:9]
	v_pk_mul_f32 v[12:13], v[12:13], v[226:227]
	v_pk_mul_f32 v[10:11], v[10:11], v[224:225]
	s_nop 1
	s_waitcnt lgkmcnt(0)
	v_mfma_f32_16x16x32_bf16 v[10:13], v[176:179], v[26:29], v[10:13]
	v_mfma_f32_16x16x32_bf16 v[10:13], v[180:183], v[22:25], v[10:13]
	v_add_u32_e32 v204, s76, v41
	v_ashrrev_i32_e32 v205, 31, v204
	v_cvt_pk_bf16_f32 v248, v248, v249
	v_cvt_pk_bf16_f32 v249, v250, v251
	v_lshlrev_b64 v[250:251], 11, v[204:205]
	v_lshl_add_u64 v[250:251], v[50:51], 0, v[250:251]
	global_store_dwordx2 v[250:251], v[248:249], off nt
	v_add_u32_e32 v204, s76, v142
	v_ashrrev_i32_e32 v205, 31, v204
	v_cvt_pk_bf16_f32 v236, v236, v237
	v_cvt_pk_bf16_f32 v237, v238, v239
	v_lshlrev_b64 v[238:239], 11, v[204:205]
	v_lshl_add_u64 v[238:239], v[50:51], 0, v[238:239]
	global_store_dwordx2 v[238:239], v[236:237], off nt
	s_branch .LBB0_1316
.Lgl_su:
	ds_read_b128 v[176:179], v101
	ds_read_b128 v[180:183], v106 offset:34816
	ds_read_b128 v[184:187], v106 offset:34880
	ds_read_b128 v[188:191], v101 offset:64
	ds_read_b128 v[192:195], v107 offset:34816
	ds_read_b128 v[196:199], v107 offset:34880
	ds_read_b128 v[200:203], v101 offset:128
	ds_read_b128 v[216:219], v108 offset:34816
	ds_read_b128 v[220:223], v108 offset:34880
	ds_read_b128 v[224:227], v101 offset:192
	ds_read_b128 v[236:239], v109 offset:34816
	ds_read_b128 v[248:251], v109 offset:34880
	s_waitcnt lgkmcnt(10)
	v_pk_mul_f32 v[4:5], v[4:5], v[178:179]
	v_pk_mul_f32 v[2:3], v[2:3], v[176:177]
	s_nop 1
	v_mfma_f32_16x16x32_bf16 v[2:5], v[180:183], v[26:29], v[2:5]
	s_waitcnt lgkmcnt(8)
	v_mfma_f32_16x16x32_bf16 v[2:5], v[184:187], v[22:25], v[2:5]
	v_pk_mul_f32 v[16:17], v[16:17], v[190:191]
	v_pk_mul_f32 v[14:15], v[14:15], v[188:189]
	s_nop 1
	s_waitcnt lgkmcnt(6)
	v_mfma_f32_16x16x32_bf16 v[14:17], v[192:195], v[26:29], v[14:17]
	v_mfma_f32_16x16x32_bf16 v[14:17], v[196:199], v[22:25], v[14:17]
	s_waitcnt lgkmcnt(4)
	v_pk_mul_f32 v[8:9], v[8:9], v[202:203]
	v_pk_mul_f32 v[6:7], v[6:7], v[200:201]
	s_nop 1
	v_mfma_f32_16x16x32_bf16 v[6:9], v[216:219], v[26:29], v[6:9]
	s_waitcnt lgkmcnt(2)
	v_mfma_f32_16x16x32_bf16 v[6:9], v[220:223], v[22:25], v[6:9]
	v_pk_mul_f32 v[12:13], v[12:13], v[226:227]
	v_pk_mul_f32 v[10:11], v[10:11], v[224:225]
	s_nop 1
	s_waitcnt lgkmcnt(0)
	v_mfma_f32_16x16x32_bf16 v[10:13], v[236:239], v[26:29], v[10:13]
	v_mfma_f32_16x16x32_bf16 v[10:13], v[248:251], v[22:25], v[10:13]
	s_branch .LBB0_1316
